# grid barrier: followers poll the top-level generation word and the XCD leader no longer publishes (and waits on) a per-XCD generation word
# baseline (speedup 1.0000x reference)
.LBB0_16:
	s_or_b64 exec, exec, s[4:5]
	v_add_co_u32_e32 v2, vcc, 0x2000, v4
	s_waitcnt vmcnt(0) lgkmcnt(0)
	buffer_inv sc1
	v_addc_co_u32_e32 v3, vcc, 0, v5, vcc
	s_waitcnt vmcnt(0)
